# p2 mix phase: workgroups with bit 3 of their id set run their 18-item list in reverse (misc items first, SSD item last) so L2-heavy items overlap the other half's latency-bound SSD items
# baseline (speedup 1.0000x reference)
; DI void phase_mix(const Params& P, unsigned char* smem) {
;     constexpr int I_SSD = 256, I_KV = 1024, I_CMP = 256, I_WT = 3 * 1024;
;     constexpr int NIT = I_SSD + I_KV + I_CMP + I_WT;
;     for (int it = blockIdx.x; it < NIT; it += gridDim.x) {
;         int r = it;
;         if (r < I_SSD) { ssd_pair_item(P, smem, r >> 4, r & 15); __syncthreads(); continue; } r -= I_SSD;
;         if (r < I_KV) { kvprep_item(P, smem, r); continue; } r -= I_KV;
;         if (r < I_CMP) { compress_item(P, smem, r); continue; } r -= I_CMP;
.LBB0_233:
	s_or_b64 exec, exec, s[2:3]
	s_cmpk_gt_i32 s6, 0x11ff
	s_waitcnt lgkmcnt(0)
	s_barrier
	s_cbranch_scc1 .LBB0_321
	s_add_u32 s8, s30, 0x3c000000
	s_addc_u32 s9, s31, 0
	s_add_u32 s16, s30, 0x3b001000
	s_addc_u32 s17, s31, 0
	s_cmp_lg_u64 s[36:37], 0
	s_cselect_b64 s[46:47], -1, 0
	s_add_u32 s48, s30, 0x3ee12000
	s_addc_u32 s49, s31, 0
	s_add_u32 s50, s30, 0x3ed12000
	s_addc_u32 s51, s31, 0
	s_add_u32 s52, s30, 0x3c800000
	s_addc_u32 s53, s31, 0
	s_add_u32 s54, s30, 0x3d800000
	s_addc_u32 s55, s31, 0
	s_add_u32 s56, s30, 0x3ef12000
	s_addc_u32 s57, s31, 0
	s_lshl_b32 s0, s6, 5
	v_writelane_b32 v236, s87, 2
	s_add_i32 s76, s6, 0xfffffb00
	s_add_i32 s77, s0, 0xffff6000
	s_lshl_b32 s78, s10, 5
	s_movk_i32 s79, 0xff
	s_mov_b32 s59, 0
	v_mov_b32_e32 v65, 0
	s_movk_i32 s80, 0x104
	s_movk_i32 s81, 0x100
	s_movk_i32 s83, 0x7600
	s_movk_i32 s84, 0x110
	v_mov_b32_e32 v178, 0x358637bd
	s_mov_b32 s86, 0xf800000
	v_mov_b32_e32 v179, 0x260
	s_movk_i32 s87, 0x3b00
	s_add_i32 s88, 0, 0x13b00
	s_mov_b64 s[60:61], 0x1000
	v_mov_b32_e32 v180, 0x3ecc95a3
	s_mov_b32 s89, 0x7f800000
	s_mov_b32 s90, 0x33800000
	s_add_i32 s91, 0, 0x4400
	s_movk_i32 s92, 0x90
	s_movk_i32 s93, 0x1200
	v_cndmask_b32_e64 v181, 0, 1, s[46:47]
	s_mov_b32 s94, 0x5040100
	v_mbcnt_hi_u32_b32 v182, -1, v173
	v_mov_b32_e32 v183, 0x7e0
	v_mov_b32_e32 v152, 0x3f317218
	v_mov_b32_e32 v184, 0x7f800000
	v_mov_b32_e32 v185, 0x7fc00000
	v_mov_b32_e32 v186, 0xff800000
	v_bfrev_b32_e32 v187, 0.5
	s_mov_b32 s95, s6
	s_mov_b32 s96, s6
	s_mov_b64 s[68:69], 0x17200
	s_mov_b32 s99, s10
	s_mov_b32 s100, s78
	s_bitcmp1_b32 s6, 3
	s_cbranch_scc0 .Lp2_fwd
	s_mul_i32 s98, s10, 17
	s_add_i32 s96, s96, s98
	s_add_i32 s95, s95, s98
	s_add_i32 s76, s76, s98
	s_mul_i32 s98, s78, 17
	s_add_i32 s77, s77, s98
	s_sub_i32 s99, 0, s10
	s_sub_i32 s100, 0, s78
.Lp2_fwd:
	s_branch .LBB0_237
.LBB0_235:
	s_barrier
.LBB0_236:
	s_add_i32 s96, s96, s99
	s_add_i32 s76, s76, s99
	s_add_i32 s77, s77, s100
	s_add_i32 s95, s95, s99
	s_cmpk_lt_u32 s96, 0x1200
	s_cbranch_scc0 .LBB0_320
